# grid barrier: the L1 invalidate of the acquire side is issued when a workgroup arrives (before it polls / together with the leader's L2 write-back) instead of after the generation flips
# speedup vs baseline: 1.0171x; 1.0171x over previous
; __device__ __forceinline__ unsigned xb_ld(unsigned* p)              { return __hip_atomic_load(p, __ATOMIC_RELAXED, __HIP_MEMORY_SCOPE_AGENT); }
; __device__ __forceinline__ unsigned xb_add(unsigned* p, unsigned v) { return __hip_atomic_fetch_add(p, v, __ATOMIC_RELAXED, __HIP_MEMORY_SCOPE_AGENT); }
; #define XB_SPIN(cond, bar) do { unsigned _sp = 0; while (cond) { __builtin_amdgcn_s_sleep(1); \
;     if ((++_sp & 255u) == 0u) { if (xb_ld(&(bar)[XB_TMO])) break; if (_sp > XB_SPIN_CAP) { atomicAdd(&(bar)[XB_TMO], 1u); break; } } } } while (0)
; __device__ __forceinline__ void xcd_barrier(const XcdBarrier& b) {
;     ...
;         const unsigned old = xb_add(&bar[XB_XSUB(b.x)], 1u);
;         const unsigned gen = old / nloc;
;         if (old + 1u == (gen + 1u) * nloc) {
;             __builtin_amdgcn_fence(__ATOMIC_RELEASE, "agent");
;             asm volatile("s_waitcnt vmcnt(0)" ::: "memory");
;             const unsigned og = xb_add(&bar[XB_TOP], 1u);
;             const unsigned tg = og / nx;
;             if (og + 1u == (tg + 1u) * nx) xb_add(&bar[XB_TOPGEN], 1u);
;             else XB_SPIN(xb_ld(&bar[XB_TOPGEN]) == tg, bar);
;             __builtin_amdgcn_fence(__ATOMIC_ACQUIRE, "agent");
;             xb_add(&bar[XB_XGEN(b.x)], 1u);
;             asm volatile("s_waitcnt vmcnt(0)" ::: "memory");
;         } else {
;             XB_SPIN(xb_ld(&bar[XB_XGEN(b.x)]) == gen, bar);
;             __builtin_amdgcn_fence(__ATOMIC_ACQUIRE, "agent");
.LBB0_72:
	s_or_b64 exec, exec, s[2:3]
	v_cvt_f32_u32_e32 v4, v2
	s_waitcnt vmcnt(0)
	v_readfirstlane_b32 s2, v3
	v_sub_u32_e32 v3, 0, v2
	v_rcp_iflag_f32_e32 v4, v4
	v_add_u32_e32 v5, s2, v1
	v_mul_f32_e32 v4, 0x4f7ffffe, v4
	v_cvt_u32_f32_e32 v4, v4
	v_mul_lo_u32 v1, v3, v4
	v_mul_hi_u32 v1, v4, v1
	v_add_u32_e32 v1, v4, v1
	v_mul_hi_u32 v1, v5, v1
	v_mul_lo_u32 v3, v1, v2
	v_sub_u32_e32 v3, v5, v3
	v_add_u32_e32 v4, 1, v1
	v_cmp_ge_u32_e32 vcc, v3, v2
	s_nop 1
	v_cndmask_b32_e32 v1, v1, v4, vcc
	v_sub_u32_e32 v4, v3, v2
	v_cndmask_b32_e32 v3, v3, v4, vcc
	v_add_u32_e32 v4, 1, v1
	v_cmp_ge_u32_e32 vcc, v3, v2
	v_add_u32_e32 v3, 1, v5
	s_nop 0
	v_cndmask_b32_e32 v1, v1, v4, vcc
	v_mul_lo_u32 v4, v2, v1
	v_add_u32_e32 v2, v4, v2
	v_cmp_ne_u32_e32 vcc, v3, v2
	s_and_saveexec_b64 s[2:3], vcc
	s_xor_b64 s[2:3], exec, s[2:3]
	s_cbranch_execz .LBB0_86
	v_readlane_b32 s4, v253, 2
	s_waitcnt lgkmcnt(0)
	v_mov_b32_e32 v0, 0
	v_readlane_b32 s5, v253, 3
	s_nop 4
	buffer_inv sc1
	global_load_dword v2, v0, s[4:5] sc1
	s_waitcnt vmcnt(0)
	v_cmp_eq_u32_e32 vcc, v2, v1
	s_and_saveexec_b64 s[4:5], vcc
	s_cbranch_execz .LBB0_85
	s_mov_b32 s15, 1
	s_mov_b64 s[6:7], 0
	s_branch .LBB0_76

; __device__ __forceinline__ unsigned xb_ld(unsigned* p)              { return __hip_atomic_load(p, __ATOMIC_RELAXED, __HIP_MEMORY_SCOPE_AGENT); }
; __device__ __forceinline__ unsigned xb_add(unsigned* p, unsigned v) { return __hip_atomic_fetch_add(p, v, __ATOMIC_RELAXED, __HIP_MEMORY_SCOPE_AGENT); }
; #define XB_SPIN(cond, bar) do { unsigned _sp = 0; while (cond) { __builtin_amdgcn_s_sleep(1); \
;     if ((++_sp & 255u) == 0u) { if (xb_ld(&(bar)[XB_TMO])) break; if (_sp > XB_SPIN_CAP) { atomicAdd(&(bar)[XB_TMO], 1u); break; } } } } while (0)
; __device__ __forceinline__ void xcd_barrier(const XcdBarrier& b) {
;     ...
;         if (old + 1u == (gen + 1u) * nloc) {
;             __builtin_amdgcn_fence(__ATOMIC_RELEASE, "agent");
;             asm volatile("s_waitcnt vmcnt(0)" ::: "memory");
;             const unsigned og = xb_add(&bar[XB_TOP], 1u);
;             const unsigned tg = og / nx;
;             if (og + 1u == (tg + 1u) * nx) xb_add(&bar[XB_TOPGEN], 1u);
;             else XB_SPIN(xb_ld(&bar[XB_TOPGEN]) == tg, bar);
;             __builtin_amdgcn_fence(__ATOMIC_ACQUIRE, "agent");
.LBB0_85:
	s_or_b64 exec, exec, s[4:5]
	s_waitcnt vmcnt(0)
	s_waitcnt vmcnt(0)
.LBB0_86:
	s_andn2_saveexec_b64 s[2:3], s[2:3]
	s_cbranch_execz .LBB0_106
	s_mov_b64 s[2:3], exec
	buffer_wbl2 sc1
	buffer_inv sc1
	s_waitcnt lgkmcnt(0)
	s_waitcnt vmcnt(0)
	v_mbcnt_lo_u32_b32 v1, s2, 0
	v_mbcnt_hi_u32_b32 v1, s3, v1
	v_cmp_eq_u32_e32 vcc, 0, v1
	s_and_saveexec_b64 s[4:5], vcc
	s_cbranch_execz .LBB0_89
	s_bcnt1_i32_b64 s2, s[2:3]
	v_mov_b32_e32 v3, s2
	v_readlane_b32 s2, v253, 0
	v_mov_b32_e32 v2, 0
	v_readlane_b32 s3, v253, 1
	s_nop 4
	global_atomic_add v2, v2, v3, s[2:3] sc0

; __device__ __forceinline__ unsigned xb_ld(unsigned* p)              { return __hip_atomic_load(p, __ATOMIC_RELAXED, __HIP_MEMORY_SCOPE_AGENT); }
; __device__ __forceinline__ unsigned xb_add(unsigned* p, unsigned v) { return __hip_atomic_fetch_add(p, v, __ATOMIC_RELAXED, __HIP_MEMORY_SCOPE_AGENT); }
; #define XB_SPIN(cond, bar) do { unsigned _sp = 0; while (cond) { __builtin_amdgcn_s_sleep(1); \
;     if ((++_sp & 255u) == 0u) { if (xb_ld(&(bar)[XB_TMO])) break; if (_sp > XB_SPIN_CAP) { atomicAdd(&(bar)[XB_TMO], 1u); break; } } } } while (0)
; __device__ __forceinline__ void xcd_barrier(const XcdBarrier& b) {
;     ...
;             if (og + 1u == (tg + 1u) * nx) xb_add(&bar[XB_TOPGEN], 1u);
;             else XB_SPIN(xb_ld(&bar[XB_TOPGEN]) == tg, bar);
;             __builtin_amdgcn_fence(__ATOMIC_ACQUIRE, "agent");
;             xb_add(&bar[XB_XGEN(b.x)], 1u);
.LBB0_103:
	s_or_b64 exec, exec, s[2:3]
	s_mov_b64 s[2:3], exec
	v_mbcnt_lo_u32_b32 v0, s2, 0
	v_mbcnt_hi_u32_b32 v0, s3, v0
	v_cmp_eq_u32_e32 vcc, 0, v0
	s_waitcnt vmcnt(0)
	s_and_saveexec_b64 s[4:5], vcc
	s_cbranch_execz .LBB0_105
	s_bcnt1_i32_b64 s2, s[2:3]
	v_mov_b32_e32 v1, s2
	v_readlane_b32 s2, v252, 62
	v_mov_b32_e32 v0, 0
	v_readlane_b32 s3, v252, 63
	s_nop 4
	global_atomic_add v0, v1, s[2:3]

; __device__ __forceinline__ unsigned xb_ld(unsigned* p)              { return __hip_atomic_load(p, __ATOMIC_RELAXED, __HIP_MEMORY_SCOPE_AGENT); }
; __device__ __forceinline__ unsigned xb_add(unsigned* p, unsigned v) { return __hip_atomic_fetch_add(p, v, __ATOMIC_RELAXED, __HIP_MEMORY_SCOPE_AGENT); }
; #define XB_SPIN(cond, bar) do { unsigned _sp = 0; while (cond) { __builtin_amdgcn_s_sleep(1); \
;     if ((++_sp & 255u) == 0u) { if (xb_ld(&(bar)[XB_TMO])) break; if (_sp > XB_SPIN_CAP) { atomicAdd(&(bar)[XB_TMO], 1u); break; } } } } while (0)
; __device__ __forceinline__ void xcd_barrier(const XcdBarrier& b) {
;     ...
;         const unsigned old = xb_add(&bar[XB_XSUB(b.x)], 1u);
;         const unsigned gen = old / nloc;
;         if (old + 1u == (gen + 1u) * nloc) {
;             __builtin_amdgcn_fence(__ATOMIC_RELEASE, "agent");
;             asm volatile("s_waitcnt vmcnt(0)" ::: "memory");
;             const unsigned og = xb_add(&bar[XB_TOP], 1u);
;             const unsigned tg = og / nx;
;             if (og + 1u == (tg + 1u) * nx) xb_add(&bar[XB_TOPGEN], 1u);
;             else XB_SPIN(xb_ld(&bar[XB_TOPGEN]) == tg, bar);
;             __builtin_amdgcn_fence(__ATOMIC_ACQUIRE, "agent");
;             xb_add(&bar[XB_XGEN(b.x)], 1u);
;             asm volatile("s_waitcnt vmcnt(0)" ::: "memory");
;         } else {
;             XB_SPIN(xb_ld(&bar[XB_XGEN(b.x)]) == gen, bar);
;             __builtin_amdgcn_fence(__ATOMIC_ACQUIRE, "agent");
.LBB0_242:
	s_or_b64 exec, exec, s[12:13]
	v_cvt_f32_u32_e32 v4, v2
	s_waitcnt vmcnt(0)
	v_readfirstlane_b32 s0, v3
	v_sub_u32_e32 v3, 0, v2
	v_rcp_iflag_f32_e32 v4, v4
	v_add_u32_e32 v5, s0, v1
	v_mul_f32_e32 v4, 0x4f7ffffe, v4
	v_cvt_u32_f32_e32 v4, v4
	v_mul_lo_u32 v1, v3, v4
	v_mul_hi_u32 v1, v4, v1
	v_add_u32_e32 v1, v4, v1
	v_mul_hi_u32 v1, v5, v1
	v_mul_lo_u32 v3, v1, v2
	v_sub_u32_e32 v3, v5, v3
	v_add_u32_e32 v4, 1, v1
	v_cmp_ge_u32_e32 vcc, v3, v2
	s_nop 1
	v_cndmask_b32_e32 v1, v1, v4, vcc
	v_sub_u32_e32 v4, v3, v2
	v_cndmask_b32_e32 v3, v3, v4, vcc
	v_add_u32_e32 v4, 1, v1
	v_cmp_ge_u32_e32 vcc, v3, v2
	v_add_u32_e32 v3, 1, v5
	s_nop 0
	v_cndmask_b32_e32 v1, v1, v4, vcc
	v_mul_lo_u32 v4, v2, v1
	v_add_u32_e32 v2, v4, v2
	v_cmp_ne_u32_e32 vcc, v3, v2
	s_and_saveexec_b64 s[12:13], vcc
	s_xor_b64 s[12:13], exec, s[12:13]
	s_cbranch_execz .LBB0_256
	v_readlane_b32 s24, v253, 2
	v_readlane_b32 s25, v253, 3
	s_waitcnt lgkmcnt(0)
	s_nop 3
	buffer_inv sc1
	global_load_dword v0, v185, s[24:25] sc1
	s_waitcnt vmcnt(0)
	v_cmp_eq_u32_e32 vcc, v0, v1
	s_and_saveexec_b64 s[24:25], vcc
	s_cbranch_execz .LBB0_255
	s_mov_b32 s0, 1
	s_mov_b64 s[26:27], 0
	s_branch .LBB0_246

; __device__ __forceinline__ unsigned xb_ld(unsigned* p)              { return __hip_atomic_load(p, __ATOMIC_RELAXED, __HIP_MEMORY_SCOPE_AGENT); }
; __device__ __forceinline__ unsigned xb_add(unsigned* p, unsigned v) { return __hip_atomic_fetch_add(p, v, __ATOMIC_RELAXED, __HIP_MEMORY_SCOPE_AGENT); }
; #define XB_SPIN(cond, bar) do { unsigned _sp = 0; while (cond) { __builtin_amdgcn_s_sleep(1); \
;     if ((++_sp & 255u) == 0u) { if (xb_ld(&(bar)[XB_TMO])) break; if (_sp > XB_SPIN_CAP) { atomicAdd(&(bar)[XB_TMO], 1u); break; } } } } while (0)
; __device__ __forceinline__ void xcd_barrier(const XcdBarrier& b) {
;     ...
;         if (old + 1u == (gen + 1u) * nloc) {
;             __builtin_amdgcn_fence(__ATOMIC_RELEASE, "agent");
;             asm volatile("s_waitcnt vmcnt(0)" ::: "memory");
;             const unsigned og = xb_add(&bar[XB_TOP], 1u);
;             const unsigned tg = og / nx;
;             if (og + 1u == (tg + 1u) * nx) xb_add(&bar[XB_TOPGEN], 1u);
;             else XB_SPIN(xb_ld(&bar[XB_TOPGEN]) == tg, bar);
;             __builtin_amdgcn_fence(__ATOMIC_ACQUIRE, "agent");
.LBB0_255:
	s_or_b64 exec, exec, s[24:25]
	s_waitcnt vmcnt(0)
	s_waitcnt vmcnt(0)
.LBB0_256:
	s_andn2_saveexec_b64 s[12:13], s[12:13]
	s_cbranch_execz .LBB0_276
	s_mov_b64 s[12:13], exec
	buffer_wbl2 sc1
	buffer_inv sc1
	s_waitcnt lgkmcnt(0)
	s_waitcnt vmcnt(0)
	v_mbcnt_lo_u32_b32 v1, s12, 0
	v_mbcnt_hi_u32_b32 v1, s13, v1
	v_cmp_eq_u32_e32 vcc, 0, v1
	s_and_saveexec_b64 s[24:25], vcc
	s_cbranch_execz .LBB0_259
	s_bcnt1_i32_b64 s0, s[12:13]
	v_readlane_b32 s12, v253, 0
	v_mov_b32_e32 v2, s0
	v_readlane_b32 s13, v253, 1
	s_nop 4
	global_atomic_add v2, v185, v2, s[12:13] sc0

; __device__ __forceinline__ unsigned xb_ld(unsigned* p)              { return __hip_atomic_load(p, __ATOMIC_RELAXED, __HIP_MEMORY_SCOPE_AGENT); }
; __device__ __forceinline__ unsigned xb_add(unsigned* p, unsigned v) { return __hip_atomic_fetch_add(p, v, __ATOMIC_RELAXED, __HIP_MEMORY_SCOPE_AGENT); }
; #define XB_SPIN(cond, bar) do { unsigned _sp = 0; while (cond) { __builtin_amdgcn_s_sleep(1); \
;     if ((++_sp & 255u) == 0u) { if (xb_ld(&(bar)[XB_TMO])) break; if (_sp > XB_SPIN_CAP) { atomicAdd(&(bar)[XB_TMO], 1u); break; } } } } while (0)
; __device__ __forceinline__ void xcd_barrier(const XcdBarrier& b) {
;     ...
;             if (og + 1u == (tg + 1u) * nx) xb_add(&bar[XB_TOPGEN], 1u);
;             else XB_SPIN(xb_ld(&bar[XB_TOPGEN]) == tg, bar);
;             __builtin_amdgcn_fence(__ATOMIC_ACQUIRE, "agent");
;             xb_add(&bar[XB_XGEN(b.x)], 1u);
.LBB0_273:
	s_or_b64 exec, exec, s[12:13]
	s_mov_b64 s[12:13], exec
	v_mbcnt_lo_u32_b32 v0, s12, 0
	v_mbcnt_hi_u32_b32 v0, s13, v0
	v_cmp_eq_u32_e32 vcc, 0, v0
	s_waitcnt vmcnt(0)
	s_and_saveexec_b64 s[24:25], vcc
	s_cbranch_execz .LBB0_275
	s_bcnt1_i32_b64 s0, s[12:13]
	v_readlane_b32 s12, v252, 62
	v_mov_b32_e32 v0, s0
	v_readlane_b32 s13, v252, 63
	s_nop 4
	global_atomic_add v185, v0, s[12:13]

; __device__ __forceinline__ unsigned xb_add(unsigned* p, unsigned v) { return __hip_atomic_fetch_add(p, v, __ATOMIC_RELAXED, __HIP_MEMORY_SCOPE_AGENT); }
; __device__ __forceinline__ void xcd_barrier(const XcdBarrier& b) {
;     ...
;         if (old + 1u == (gen + 1u) * nloc) {
;             __builtin_amdgcn_fence(__ATOMIC_RELEASE, "agent");
;             asm volatile("s_waitcnt vmcnt(0)" ::: "memory");
;             const unsigned og = xb_add(&bar[XB_TOP], 1u);
;             const unsigned tg = og / nx;
.LBB0_1681:
	s_mov_b64 s[12:13], exec
	buffer_wbl2 sc1
	buffer_inv sc1
	s_waitcnt lgkmcnt(0)
	s_waitcnt vmcnt(0)
	v_mbcnt_lo_u32_b32 v1, s12, 0
	v_mbcnt_hi_u32_b32 v1, s13, v1
	v_cmp_eq_u32_e32 vcc, 0, v1
	s_and_saveexec_b64 s[24:25], vcc
	s_cbranch_execz .LBB0_1683
	s_bcnt1_i32_b64 s0, s[12:13]
	v_readlane_b32 s12, v253, 0
	v_mov_b32_e32 v2, s0
	v_readlane_b32 s13, v253, 1
	s_nop 4
	global_atomic_add v2, v185, v2, s[12:13] sc0

; __device__ __forceinline__ unsigned xb_ld(unsigned* p)              { return __hip_atomic_load(p, __ATOMIC_RELAXED, __HIP_MEMORY_SCOPE_AGENT); }
; __device__ __forceinline__ unsigned xb_add(unsigned* p, unsigned v) { return __hip_atomic_fetch_add(p, v, __ATOMIC_RELAXED, __HIP_MEMORY_SCOPE_AGENT); }
; #define XB_SPIN(cond, bar) do { unsigned _sp = 0; while (cond) { __builtin_amdgcn_s_sleep(1); \
;     if ((++_sp & 255u) == 0u) { if (xb_ld(&(bar)[XB_TMO])) break; if (_sp > XB_SPIN_CAP) { atomicAdd(&(bar)[XB_TMO], 1u); break; } } } } while (0)
; __device__ __forceinline__ void xcd_barrier(const XcdBarrier& b) {
;     ...
;             if (og + 1u == (tg + 1u) * nx) xb_add(&bar[XB_TOPGEN], 1u);
;             else XB_SPIN(xb_ld(&bar[XB_TOPGEN]) == tg, bar);
;             __builtin_amdgcn_fence(__ATOMIC_ACQUIRE, "agent");
;             xb_add(&bar[XB_XGEN(b.x)], 1u);
.LBB0_1697:
	s_or_b64 exec, exec, s[12:13]
	s_mov_b64 s[12:13], exec
	v_mbcnt_lo_u32_b32 v0, s12, 0
	v_mbcnt_hi_u32_b32 v0, s13, v0
	v_cmp_eq_u32_e32 vcc, 0, v0
	s_waitcnt vmcnt(0)
	s_and_saveexec_b64 s[24:25], vcc
	s_cbranch_execnz .LBB0_1698
	s_getpc_b64 s[98:99]
